# speedup vs baseline: 1.0016x; 1.0016x over previous
; __device__ __forceinline__ float u8f(unsigned w, int i) { return (float)((w >> (8 * i)) & 0xffu) * (1.f / 255.f); }
; #define EPI_BEGIN_S int fo_e = fo, to_e = to; asm volatile("" : "+s"(fo_e), "+s"(to_e));
; __device__ __forceinline__ void gemm_tile(const u16* __restrict__ A, const u16* __restrict__ Bt, const int K,
;                                           const int brow, const int bcol, f32x4 (&acc)[2][2][4][2],
;                                           const bool ZERO_INIT = true) {
;     ...
;   STAGE(SB(0, 0), Bt, bcol, 0); STAGE(SA(0, 0), A, brow, 0);
;   STAGE(SB(0, 1), Bt, bcol + HALF, 0); STAGE(SA(0, 1), A, brow + HALF, 0);
; __device__ void phase4(const Params& p) {
;     ...
;       gemm_tile(Wp, Xp, Kp, fo, to, acc, seg == 0);
;       EPI_BEGIN_S
;       const size_t lanef = (size_t)(fo_e + wr * 64 + fq * 4);
;       if (seg == 0) {
;         #pragma unroll
;         for (int bj = 0; bj < 2; ++bj)
;           #pragma unroll
;           for (int n = 0; n < 2; ++n) {
;             const size_t base = (size_t)EPI_T(bj, n) * D + lanef;
;             const unsigned* pa = reinterpret_cast<const unsigned*>(reinterpret_cast<const unsigned char*>(sga) + base);
;             const unsigned* pb = reinterpret_cast<const unsigned*>(reinterpret_cast<const unsigned char*>(sgb) + base);
;             #pragma unroll
;             for (int ai = 0; ai < 2; ++ai)
;               #pragma unroll
;               for (int m = 0; m < 4; ++m) {
;                 const unsigned ga = pa[(ai * 128 + m * 16) / 4];
;                 const unsigned gb = pb[(ai * 128 + m * 16) / 4];
;                 #pragma unroll
;                 for (int j = 0; j < 4; ++j)
;                   acc[ai][bj][m][n][j] *= u8f(ga, j) * __builtin_amdgcn_rcpf(fmaxf(u8f(gb, j), 1e-30f));
;               }
.LBB0_608:
	s_or_b64 exec, exec, s[50:51]
	v_and_b32_e32 v132, 15, v194
	v_lshrrev_b32_e32 v133, 1, v194
	v_and_b32_e32 v133, 0x60, v133
	v_add3_u32 v132, s18, v132, v133
	v_bfe_u32 v134, v194, 4, 2
	v_lshrrev_b32_e32 v135, 2, v194
	v_and_b32_e32 v135, 0xffffffc0, v135
	v_lshl_add_u32 v136, v134, 4, v135
	v_add_u32_e32 v136, s20, v136
	v_lshl_add_u32 v136, v132, 11, v136
	v_add_u32_e32 v137, 0x8000, v136
	v_add_u32_e32 v138, 0x40000, v136
	v_add_u32_e32 v139, 0x48000, v136
	s_cmp_lg_u32 s79, 0
	s_cbranch_scc1 .Lp4e_seg1
	v_lshrrev_b32_e32 v248, 1, v246
	v_lshrrev_b32_e32 v250, 11, v248
	v_and_b32_e32 v248, 0x7ff, v248
	v_lshl_add_u32 v248, v250, 10, v248
	v_lshlrev_b32_e32 v250, 1, v248
	v_lshrrev_b32_e32 v249, 1, v247
	v_lshrrev_b32_e32 v251, 11, v249
	v_and_b32_e32 v249, 0x7ff, v249
	v_lshl_add_u32 v249, v251, 10, v249
	v_lshlrev_b32_e32 v251, 1, v249
	s_lshl_b32 s54, s18, 11
	s_add_u32 s58, s44, s54
	s_addc_u32 s59, s45, 0
	s_or_b32 s55, s18, 0x80
	s_lshl_b32 s55, s55, 11
	s_add_u32 s60, s44, s55
	s_addc_u32 s61, s45, 0
	s_lshl_b32 s54, s20, 11
	s_add_u32 s54, s54, 0x3100000
	s_add_u32 s62, s30, s54
	s_addc_u32 s63, s31, 0
	s_or_b32 s55, s20, 0x80
	s_lshl_b32 s55, s55, 11
	s_add_u32 s55, s55, 0x3100000
	s_add_u32 s64, s30, s55
	s_addc_u32 s65, s31, 0
	v_lshrrev_b32_e32 v252, 6, v194
	s_nop 0
	v_readfirstlane_b32 s66, v252
	s_nop 3
	s_lshl_b32 s66, s66, 10
	s_add_u32 m0, s66, 0x10000
	s_nop 0
	global_load_lds_dwordx4 v250, s[58:59]
	s_add_u32 m0, s66, 0x12000
	s_nop 0
	global_load_lds_dwordx4 v251, s[58:59]
	s_add_u32 m0, s66, 0x0
	s_nop 0
	global_load_lds_dwordx4 v250, s[62:63]
	s_add_u32 m0, s66, 0x2000
	s_nop 0
	global_load_lds_dwordx4 v251, s[62:63]
	s_add_u32 m0, s66, 0x14000
	s_nop 0
	global_load_lds_dwordx4 v250, s[60:61]
	s_add_u32 m0, s66, 0x16000
	s_nop 0
	global_load_lds_dwordx4 v251, s[60:61]
	s_add_u32 m0, s66, 0x4000
	s_nop 0
	global_load_lds_dwordx4 v250, s[64:65]
	s_add_u32 m0, s66, 0x6000
	s_nop 0
	global_load_lds_dwordx4 v251, s[64:65]
	s_mov_b32 s100, 1
	global_load_dwordx4 v[152:155], v136, s[10:11]
	global_load_dwordx4 v[156:159], v136, s[12:13]
	global_load_dwordx4 v[160:163], v136, s[10:11] offset:128
	global_load_dwordx4 v[164:167], v136, s[12:13] offset:128
	global_load_dwordx4 v[168:171], v137, s[10:11]
	global_load_dwordx4 v[172:175], v137, s[12:13]
	global_load_dwordx4 v[176:179], v137, s[10:11] offset:128
	global_load_dwordx4 v[180:183], v137, s[12:13] offset:128
	global_load_dwordx4 v[184:187], v138, s[10:11]
	global_load_dwordx4 v[188:191], v138, s[12:13]
	global_load_dwordx4 v[196:199], v138, s[10:11] offset:128
	global_load_dwordx4 v[200:203], v138, s[12:13] offset:128
	global_load_dwordx4 v[204:207], v139, s[10:11]
	global_load_dwordx4 v[208:211], v139, s[12:13]
	global_load_dwordx4 v[212:215], v139, s[10:11] offset:128
	global_load_dwordx4 v[216:219], v139, s[12:13] offset:128
	s_waitcnt vmcnt(14)
	v_permlane16_swap_b32 v152, v153
	v_permlane16_swap_b32 v154, v155
	v_permlane16_swap_b32 v156, v157
	v_permlane16_swap_b32 v158, v159
	v_permlane32_swap_b32 v152, v154
	v_permlane32_swap_b32 v153, v155
	v_permlane32_swap_b32 v156, v158
	v_permlane32_swap_b32 v157, v159
	v_cvt_f32_ubyte0_e32 v144, v156
	v_cvt_f32_ubyte1_e32 v145, v156
	v_cvt_f32_ubyte2_e32 v146, v156
	v_cvt_f32_ubyte3_e32 v147, v156
	v_cvt_f32_ubyte0_e32 v140, v152
	v_cvt_f32_ubyte1_e32 v141, v152
	v_cvt_f32_ubyte2_e32 v142, v152
	v_cvt_f32_ubyte3_e32 v143, v152
	v_pk_mul_f32 v[144:145], v[144:145], s[16:17] op_sel_hi:[1,0]
	v_pk_mul_f32 v[146:147], v[146:147], s[16:17] op_sel_hi:[1,0]
	v_pk_mul_f32 v[140:141], v[140:141], s[16:17] op_sel_hi:[1,0]
	v_pk_mul_f32 v[142:143], v[142:143], s[16:17] op_sel_hi:[1,0]
	v_max_f32_e32 v144, 0xda24260, v144
	v_max_f32_e32 v145, 0xda24260, v145
	v_max_f32_e32 v146, 0xda24260, v146
	v_max_f32_e32 v147, 0xda24260, v147
	v_rcp_f32_e32 v144, v144
	v_rcp_f32_e32 v145, v145
	v_rcp_f32_e32 v146, v146
	v_rcp_f32_e32 v147, v147
	v_pk_mul_f32 v[140:141], v[140:141], v[144:145]
	v_pk_mul_f32 v[142:143], v[142:143], v[146:147]
	v_pk_mul_f32 v[128:129], v[128:129], v[140:141]
	v_pk_mul_f32 v[130:131], v[130:131], v[142:143]
	v_cvt_f32_ubyte0_e32 v144, v157
	v_cvt_f32_ubyte1_e32 v145, v157
	v_cvt_f32_ubyte2_e32 v146, v157
	v_cvt_f32_ubyte3_e32 v147, v157
	v_cvt_f32_ubyte0_e32 v140, v153
	v_cvt_f32_ubyte1_e32 v141, v153
	v_cvt_f32_ubyte2_e32 v142, v153
	v_cvt_f32_ubyte3_e32 v143, v153
	v_pk_mul_f32 v[144:145], v[144:145], s[16:17] op_sel_hi:[1,0]
	v_pk_mul_f32 v[146:147], v[146:147], s[16:17] op_sel_hi:[1,0]
	v_pk_mul_f32 v[140:141], v[140:141], s[16:17] op_sel_hi:[1,0]
	v_pk_mul_f32 v[142:143], v[142:143], s[16:17] op_sel_hi:[1,0]
	v_max_f32_e32 v144, 0xda24260, v144
	v_max_f32_e32 v145, 0xda24260, v145
	v_max_f32_e32 v146, 0xda24260, v146
	v_max_f32_e32 v147, 0xda24260, v147
	v_rcp_f32_e32 v144, v144
	v_rcp_f32_e32 v145, v145
	v_rcp_f32_e32 v146, v146
	v_rcp_f32_e32 v147, v147
	v_pk_mul_f32 v[140:141], v[140:141], v[144:145]
	v_pk_mul_f32 v[142:143], v[142:143], v[146:147]
	v_pk_mul_f32 v[120:121], v[120:121], v[140:141]
	v_pk_mul_f32 v[122:123], v[122:123], v[142:143]
	v_cvt_f32_ubyte0_e32 v144, v158
	v_cvt_f32_ubyte1_e32 v145, v158
	v_cvt_f32_ubyte2_e32 v146, v158
	v_cvt_f32_ubyte3_e32 v147, v158
	v_cvt_f32_ubyte0_e32 v140, v154
	v_cvt_f32_ubyte1_e32 v141, v154
	v_cvt_f32_ubyte2_e32 v142, v154
	v_cvt_f32_ubyte3_e32 v143, v154
	v_pk_mul_f32 v[144:145], v[144:145], s[16:17] op_sel_hi:[1,0]
	v_pk_mul_f32 v[146:147], v[146:147], s[16:17] op_sel_hi:[1,0]
	v_pk_mul_f32 v[140:141], v[140:141], s[16:17] op_sel_hi:[1,0]
	v_pk_mul_f32 v[142:143], v[142:143], s[16:17] op_sel_hi:[1,0]
	v_max_f32_e32 v144, 0xda24260, v144
	v_max_f32_e32 v145, 0xda24260, v145
	v_max_f32_e32 v146, 0xda24260, v146
	v_max_f32_e32 v147, 0xda24260, v147
	v_rcp_f32_e32 v144, v144
	v_rcp_f32_e32 v145, v145
	v_rcp_f32_e32 v146, v146
	v_rcp_f32_e32 v147, v147
	v_pk_mul_f32 v[140:141], v[140:141], v[144:145]
	v_pk_mul_f32 v[142:143], v[142:143], v[146:147]
	v_pk_mul_f32 v[112:113], v[112:113], v[140:141]
	v_pk_mul_f32 v[114:115], v[114:115], v[142:143]
	v_cvt_f32_ubyte0_e32 v144, v159
	v_cvt_f32_ubyte1_e32 v145, v159
	v_cvt_f32_ubyte2_e32 v146, v159
	v_cvt_f32_ubyte3_e32 v147, v159
	v_cvt_f32_ubyte0_e32 v140, v155
	v_cvt_f32_ubyte1_e32 v141, v155
	v_cvt_f32_ubyte2_e32 v142, v155
	v_cvt_f32_ubyte3_e32 v143, v155
	v_pk_mul_f32 v[144:145], v[144:145], s[16:17] op_sel_hi:[1,0]
	v_pk_mul_f32 v[146:147], v[146:147], s[16:17] op_sel_hi:[1,0]
	v_pk_mul_f32 v[140:141], v[140:141], s[16:17] op_sel_hi:[1,0]
	v_pk_mul_f32 v[142:143], v[142:143], s[16:17] op_sel_hi:[1,0]
	v_max_f32_e32 v144, 0xda24260, v144
	v_max_f32_e32 v145, 0xda24260, v145
	v_max_f32_e32 v146, 0xda24260, v146
	v_max_f32_e32 v147, 0xda24260, v147
	v_rcp_f32_e32 v144, v144
	v_rcp_f32_e32 v145, v145
	v_rcp_f32_e32 v146, v146
	v_rcp_f32_e32 v147, v147
	v_pk_mul_f32 v[140:141], v[140:141], v[144:145]
	v_pk_mul_f32 v[142:143], v[142:143], v[146:147]
	v_pk_mul_f32 v[104:105], v[104:105], v[140:141]
	v_pk_mul_f32 v[106:107], v[106:107], v[142:143]
	s_waitcnt vmcnt(12)
; __device__ __forceinline__ float u8f(unsigned w, int i) { return (float)((w >> (8 * i)) & 0xffu) * (1.f / 255.f); }
; __device__ void phase4(const Params& p) {
;     ...
;             #pragma unroll
;             for (int ai = 0; ai < 2; ++ai)
;               #pragma unroll
;               for (int m = 0; m < 4; ++m) {
;                 const unsigned ga = pa[(ai * 128 + m * 16) / 4];
;                 const unsigned gb = pb[(ai * 128 + m * 16) / 4];
;                 #pragma unroll
;                 for (int j = 0; j < 4; ++j)
;                   acc[ai][bj][m][n][j] *= u8f(ga, j) * __builtin_amdgcn_rcpf(fmaxf(u8f(gb, j), 1e-30f));
;               }
	v_permlane16_swap_b32 v160, v161
	v_permlane16_swap_b32 v162, v163
	v_permlane16_swap_b32 v164, v165
	v_permlane16_swap_b32 v166, v167
	v_permlane32_swap_b32 v160, v162
	v_permlane32_swap_b32 v161, v163
	v_permlane32_swap_b32 v164, v166
	v_permlane32_swap_b32 v165, v167
	v_cvt_f32_ubyte0_e32 v144, v164
	v_cvt_f32_ubyte1_e32 v145, v164
	v_cvt_f32_ubyte2_e32 v146, v164
	v_cvt_f32_ubyte3_e32 v147, v164
	v_cvt_f32_ubyte0_e32 v140, v160
	v_cvt_f32_ubyte1_e32 v141, v160
	v_cvt_f32_ubyte2_e32 v142, v160
	v_cvt_f32_ubyte3_e32 v143, v160
	v_pk_mul_f32 v[144:145], v[144:145], s[16:17] op_sel_hi:[1,0]
	v_pk_mul_f32 v[146:147], v[146:147], s[16:17] op_sel_hi:[1,0]
	v_pk_mul_f32 v[140:141], v[140:141], s[16:17] op_sel_hi:[1,0]
	v_pk_mul_f32 v[142:143], v[142:143], s[16:17] op_sel_hi:[1,0]
	v_max_f32_e32 v144, 0xda24260, v144
	v_max_f32_e32 v145, 0xda24260, v145
	v_max_f32_e32 v146, 0xda24260, v146
	v_max_f32_e32 v147, 0xda24260, v147
	v_rcp_f32_e32 v144, v144
	v_rcp_f32_e32 v145, v145
	v_rcp_f32_e32 v146, v146
	v_rcp_f32_e32 v147, v147
	v_pk_mul_f32 v[140:141], v[140:141], v[144:145]
	v_pk_mul_f32 v[142:143], v[142:143], v[146:147]
	v_pk_mul_f32 v[64:65], v[64:65], v[140:141]
	v_pk_mul_f32 v[66:67], v[66:67], v[142:143]
	v_cvt_f32_ubyte0_e32 v144, v165
	v_cvt_f32_ubyte1_e32 v145, v165
	v_cvt_f32_ubyte2_e32 v146, v165
	v_cvt_f32_ubyte3_e32 v147, v165
	v_cvt_f32_ubyte0_e32 v140, v161
	v_cvt_f32_ubyte1_e32 v141, v161
	v_cvt_f32_ubyte2_e32 v142, v161
	v_cvt_f32_ubyte3_e32 v143, v161
	v_pk_mul_f32 v[144:145], v[144:145], s[16:17] op_sel_hi:[1,0]
	v_pk_mul_f32 v[146:147], v[146:147], s[16:17] op_sel_hi:[1,0]
	v_pk_mul_f32 v[140:141], v[140:141], s[16:17] op_sel_hi:[1,0]
	v_pk_mul_f32 v[142:143], v[142:143], s[16:17] op_sel_hi:[1,0]
	v_max_f32_e32 v144, 0xda24260, v144
	v_max_f32_e32 v145, 0xda24260, v145
	v_max_f32_e32 v146, 0xda24260, v146
	v_max_f32_e32 v147, 0xda24260, v147
	v_rcp_f32_e32 v144, v144
	v_rcp_f32_e32 v145, v145
	v_rcp_f32_e32 v146, v146
	v_rcp_f32_e32 v147, v147
	v_pk_mul_f32 v[140:141], v[140:141], v[144:145]
	v_pk_mul_f32 v[142:143], v[142:143], v[146:147]
	v_pk_mul_f32 v[56:57], v[56:57], v[140:141]
	v_pk_mul_f32 v[58:59], v[58:59], v[142:143]
	v_cvt_f32_ubyte0_e32 v144, v166
	v_cvt_f32_ubyte1_e32 v145, v166
	v_cvt_f32_ubyte2_e32 v146, v166
	v_cvt_f32_ubyte3_e32 v147, v166
	v_cvt_f32_ubyte0_e32 v140, v162
	v_cvt_f32_ubyte1_e32 v141, v162
	v_cvt_f32_ubyte2_e32 v142, v162
	v_cvt_f32_ubyte3_e32 v143, v162
	v_pk_mul_f32 v[144:145], v[144:145], s[16:17] op_sel_hi:[1,0]
	v_pk_mul_f32 v[146:147], v[146:147], s[16:17] op_sel_hi:[1,0]
	v_pk_mul_f32 v[140:141], v[140:141], s[16:17] op_sel_hi:[1,0]
	v_pk_mul_f32 v[142:143], v[142:143], s[16:17] op_sel_hi:[1,0]
	v_max_f32_e32 v144, 0xda24260, v144
	v_max_f32_e32 v145, 0xda24260, v145
	v_max_f32_e32 v146, 0xda24260, v146
	v_max_f32_e32 v147, 0xda24260, v147
	v_rcp_f32_e32 v144, v144
	v_rcp_f32_e32 v145, v145
	v_rcp_f32_e32 v146, v146
	v_rcp_f32_e32 v147, v147
	v_pk_mul_f32 v[140:141], v[140:141], v[144:145]
	v_pk_mul_f32 v[142:143], v[142:143], v[146:147]
	v_pk_mul_f32 v[48:49], v[48:49], v[140:141]
	v_pk_mul_f32 v[50:51], v[50:51], v[142:143]
	v_cvt_f32_ubyte0_e32 v144, v167
	v_cvt_f32_ubyte1_e32 v145, v167
	v_cvt_f32_ubyte2_e32 v146, v167
	v_cvt_f32_ubyte3_e32 v147, v167
	v_cvt_f32_ubyte0_e32 v140, v163
	v_cvt_f32_ubyte1_e32 v141, v163
	v_cvt_f32_ubyte2_e32 v142, v163
	v_cvt_f32_ubyte3_e32 v143, v163
	v_pk_mul_f32 v[144:145], v[144:145], s[16:17] op_sel_hi:[1,0]
	v_pk_mul_f32 v[146:147], v[146:147], s[16:17] op_sel_hi:[1,0]
	v_pk_mul_f32 v[140:141], v[140:141], s[16:17] op_sel_hi:[1,0]
	v_pk_mul_f32 v[142:143], v[142:143], s[16:17] op_sel_hi:[1,0]
	v_max_f32_e32 v144, 0xda24260, v144
	v_max_f32_e32 v145, 0xda24260, v145
	v_max_f32_e32 v146, 0xda24260, v146
	v_max_f32_e32 v147, 0xda24260, v147
	v_rcp_f32_e32 v144, v144
	v_rcp_f32_e32 v145, v145
	v_rcp_f32_e32 v146, v146
	v_rcp_f32_e32 v147, v147
	v_pk_mul_f32 v[140:141], v[140:141], v[144:145]
	v_pk_mul_f32 v[142:143], v[142:143], v[146:147]
	v_pk_mul_f32 v[40:41], v[40:41], v[140:141]
	v_pk_mul_f32 v[42:43], v[42:43], v[142:143]
	s_waitcnt vmcnt(10)
	v_permlane16_swap_b32 v168, v169
	v_permlane16_swap_b32 v170, v171
	v_permlane16_swap_b32 v172, v173
	v_permlane16_swap_b32 v174, v175
	v_permlane32_swap_b32 v168, v170
	v_permlane32_swap_b32 v169, v171
	v_permlane32_swap_b32 v172, v174
	v_permlane32_swap_b32 v173, v175
	v_cvt_f32_ubyte0_e32 v144, v172
	v_cvt_f32_ubyte1_e32 v145, v172
	v_cvt_f32_ubyte2_e32 v146, v172
	v_cvt_f32_ubyte3_e32 v147, v172
	v_cvt_f32_ubyte0_e32 v140, v168
	v_cvt_f32_ubyte1_e32 v141, v168
	v_cvt_f32_ubyte2_e32 v142, v168
	v_cvt_f32_ubyte3_e32 v143, v168
	v_pk_mul_f32 v[144:145], v[144:145], s[16:17] op_sel_hi:[1,0]
	v_pk_mul_f32 v[146:147], v[146:147], s[16:17] op_sel_hi:[1,0]
	v_pk_mul_f32 v[140:141], v[140:141], s[16:17] op_sel_hi:[1,0]
	v_pk_mul_f32 v[142:143], v[142:143], s[16:17] op_sel_hi:[1,0]
	v_max_f32_e32 v144, 0xda24260, v144
	v_max_f32_e32 v145, 0xda24260, v145
	v_max_f32_e32 v146, 0xda24260, v146
	v_max_f32_e32 v147, 0xda24260, v147
	v_rcp_f32_e32 v144, v144
	v_rcp_f32_e32 v145, v145
	v_rcp_f32_e32 v146, v146
	v_rcp_f32_e32 v147, v147
	v_pk_mul_f32 v[140:141], v[140:141], v[144:145]
	v_pk_mul_f32 v[142:143], v[142:143], v[146:147]
	v_pk_mul_f32 v[124:125], v[124:125], v[140:141]
	v_pk_mul_f32 v[126:127], v[126:127], v[142:143]
	v_cvt_f32_ubyte0_e32 v144, v173
	v_cvt_f32_ubyte1_e32 v145, v173
	v_cvt_f32_ubyte2_e32 v146, v173
	v_cvt_f32_ubyte3_e32 v147, v173
	v_cvt_f32_ubyte0_e32 v140, v169
	v_cvt_f32_ubyte1_e32 v141, v169
	v_cvt_f32_ubyte2_e32 v142, v169
	v_cvt_f32_ubyte3_e32 v143, v169
; __device__ __forceinline__ float u8f(unsigned w, int i) { return (float)((w >> (8 * i)) & 0xffu) * (1.f / 255.f); }
; __device__ void phase4(const Params& p) {
;     ...
;             #pragma unroll
;             for (int ai = 0; ai < 2; ++ai)
;               #pragma unroll
;               for (int m = 0; m < 4; ++m) {
;                 const unsigned ga = pa[(ai * 128 + m * 16) / 4];
;                 const unsigned gb = pb[(ai * 128 + m * 16) / 4];
;                 #pragma unroll
;                 for (int j = 0; j < 4; ++j)
;                   acc[ai][bj][m][n][j] *= u8f(ga, j) * __builtin_amdgcn_rcpf(fmaxf(u8f(gb, j), 1e-30f));
;               }
	v_pk_mul_f32 v[144:145], v[144:145], s[16:17] op_sel_hi:[1,0]
	v_pk_mul_f32 v[146:147], v[146:147], s[16:17] op_sel_hi:[1,0]
	v_pk_mul_f32 v[140:141], v[140:141], s[16:17] op_sel_hi:[1,0]
	v_pk_mul_f32 v[142:143], v[142:143], s[16:17] op_sel_hi:[1,0]
	v_max_f32_e32 v144, 0xda24260, v144
	v_max_f32_e32 v145, 0xda24260, v145
	v_max_f32_e32 v146, 0xda24260, v146
	v_max_f32_e32 v147, 0xda24260, v147
	v_rcp_f32_e32 v144, v144
	v_rcp_f32_e32 v145, v145
	v_rcp_f32_e32 v146, v146
	v_rcp_f32_e32 v147, v147
	v_pk_mul_f32 v[140:141], v[140:141], v[144:145]
	v_pk_mul_f32 v[142:143], v[142:143], v[146:147]
	v_pk_mul_f32 v[116:117], v[116:117], v[140:141]
	v_pk_mul_f32 v[118:119], v[118:119], v[142:143]
	v_cvt_f32_ubyte0_e32 v144, v174
	v_cvt_f32_ubyte1_e32 v145, v174
	v_cvt_f32_ubyte2_e32 v146, v174
	v_cvt_f32_ubyte3_e32 v147, v174
	v_cvt_f32_ubyte0_e32 v140, v170
	v_cvt_f32_ubyte1_e32 v141, v170
	v_cvt_f32_ubyte2_e32 v142, v170
	v_cvt_f32_ubyte3_e32 v143, v170
	v_pk_mul_f32 v[144:145], v[144:145], s[16:17] op_sel_hi:[1,0]
	v_pk_mul_f32 v[146:147], v[146:147], s[16:17] op_sel_hi:[1,0]
	v_pk_mul_f32 v[140:141], v[140:141], s[16:17] op_sel_hi:[1,0]
	v_pk_mul_f32 v[142:143], v[142:143], s[16:17] op_sel_hi:[1,0]
	v_max_f32_e32 v144, 0xda24260, v144
	v_max_f32_e32 v145, 0xda24260, v145
	v_max_f32_e32 v146, 0xda24260, v146
	v_max_f32_e32 v147, 0xda24260, v147
	v_rcp_f32_e32 v144, v144
	v_rcp_f32_e32 v145, v145
	v_rcp_f32_e32 v146, v146
	v_rcp_f32_e32 v147, v147
	v_pk_mul_f32 v[140:141], v[140:141], v[144:145]
	v_pk_mul_f32 v[142:143], v[142:143], v[146:147]
	v_pk_mul_f32 v[108:109], v[108:109], v[140:141]
	v_pk_mul_f32 v[110:111], v[110:111], v[142:143]
	v_cvt_f32_ubyte0_e32 v144, v175
	v_cvt_f32_ubyte1_e32 v145, v175
	v_cvt_f32_ubyte2_e32 v146, v175
	v_cvt_f32_ubyte3_e32 v147, v175
	v_cvt_f32_ubyte0_e32 v140, v171
	v_cvt_f32_ubyte1_e32 v141, v171
	v_cvt_f32_ubyte2_e32 v142, v171
	v_cvt_f32_ubyte3_e32 v143, v171
	v_pk_mul_f32 v[144:145], v[144:145], s[16:17] op_sel_hi:[1,0]
	v_pk_mul_f32 v[146:147], v[146:147], s[16:17] op_sel_hi:[1,0]
	v_pk_mul_f32 v[140:141], v[140:141], s[16:17] op_sel_hi:[1,0]
	v_pk_mul_f32 v[142:143], v[142:143], s[16:17] op_sel_hi:[1,0]
	v_max_f32_e32 v144, 0xda24260, v144
	v_max_f32_e32 v145, 0xda24260, v145
	v_max_f32_e32 v146, 0xda24260, v146
	v_max_f32_e32 v147, 0xda24260, v147
	v_rcp_f32_e32 v144, v144
	v_rcp_f32_e32 v145, v145
	v_rcp_f32_e32 v146, v146
	v_rcp_f32_e32 v147, v147
	v_pk_mul_f32 v[140:141], v[140:141], v[144:145]
	v_pk_mul_f32 v[142:143], v[142:143], v[146:147]
	v_pk_mul_f32 v[100:101], v[100:101], v[140:141]
	v_pk_mul_f32 v[102:103], v[102:103], v[142:143]
	s_waitcnt vmcnt(8)
	v_permlane16_swap_b32 v176, v177
	v_permlane16_swap_b32 v178, v179
	v_permlane16_swap_b32 v180, v181
	v_permlane16_swap_b32 v182, v183
	v_permlane32_swap_b32 v176, v178
	v_permlane32_swap_b32 v177, v179
	v_permlane32_swap_b32 v180, v182
	v_permlane32_swap_b32 v181, v183
	v_cvt_f32_ubyte0_e32 v144, v180
	v_cvt_f32_ubyte1_e32 v145, v180
	v_cvt_f32_ubyte2_e32 v146, v180
	v_cvt_f32_ubyte3_e32 v147, v180
	v_cvt_f32_ubyte0_e32 v140, v176
	v_cvt_f32_ubyte1_e32 v141, v176
	v_cvt_f32_ubyte2_e32 v142, v176
	v_cvt_f32_ubyte3_e32 v143, v176
	v_pk_mul_f32 v[144:145], v[144:145], s[16:17] op_sel_hi:[1,0]
	v_pk_mul_f32 v[146:147], v[146:147], s[16:17] op_sel_hi:[1,0]
	v_pk_mul_f32 v[140:141], v[140:141], s[16:17] op_sel_hi:[1,0]
	v_pk_mul_f32 v[142:143], v[142:143], s[16:17] op_sel_hi:[1,0]
	v_max_f32_e32 v144, 0xda24260, v144
	v_max_f32_e32 v145, 0xda24260, v145
	v_max_f32_e32 v146, 0xda24260, v146
	v_max_f32_e32 v147, 0xda24260, v147
	v_rcp_f32_e32 v144, v144
	v_rcp_f32_e32 v145, v145
	v_rcp_f32_e32 v146, v146
	v_rcp_f32_e32 v147, v147
	v_pk_mul_f32 v[140:141], v[140:141], v[144:145]
	v_pk_mul_f32 v[142:143], v[142:143], v[146:147]
	v_pk_mul_f32 v[60:61], v[60:61], v[140:141]
	v_pk_mul_f32 v[62:63], v[62:63], v[142:143]
	v_cvt_f32_ubyte0_e32 v144, v181
	v_cvt_f32_ubyte1_e32 v145, v181
	v_cvt_f32_ubyte2_e32 v146, v181
	v_cvt_f32_ubyte3_e32 v147, v181
	v_cvt_f32_ubyte0_e32 v140, v177
	v_cvt_f32_ubyte1_e32 v141, v177
	v_cvt_f32_ubyte2_e32 v142, v177
	v_cvt_f32_ubyte3_e32 v143, v177
	v_pk_mul_f32 v[144:145], v[144:145], s[16:17] op_sel_hi:[1,0]
	v_pk_mul_f32 v[146:147], v[146:147], s[16:17] op_sel_hi:[1,0]
	v_pk_mul_f32 v[140:141], v[140:141], s[16:17] op_sel_hi:[1,0]
	v_pk_mul_f32 v[142:143], v[142:143], s[16:17] op_sel_hi:[1,0]
	v_max_f32_e32 v144, 0xda24260, v144
	v_max_f32_e32 v145, 0xda24260, v145
	v_max_f32_e32 v146, 0xda24260, v146
	v_max_f32_e32 v147, 0xda24260, v147
	v_rcp_f32_e32 v144, v144
	v_rcp_f32_e32 v145, v145
	v_rcp_f32_e32 v146, v146
	v_rcp_f32_e32 v147, v147
	v_pk_mul_f32 v[140:141], v[140:141], v[144:145]
	v_pk_mul_f32 v[142:143], v[142:143], v[146:147]
	v_pk_mul_f32 v[52:53], v[52:53], v[140:141]
	v_pk_mul_f32 v[54:55], v[54:55], v[142:143]
	v_cvt_f32_ubyte0_e32 v144, v182
	v_cvt_f32_ubyte1_e32 v145, v182
	v_cvt_f32_ubyte2_e32 v146, v182
	v_cvt_f32_ubyte3_e32 v147, v182
	v_cvt_f32_ubyte0_e32 v140, v178
	v_cvt_f32_ubyte1_e32 v141, v178
	v_cvt_f32_ubyte2_e32 v142, v178
	v_cvt_f32_ubyte3_e32 v143, v178
	v_pk_mul_f32 v[144:145], v[144:145], s[16:17] op_sel_hi:[1,0]
	v_pk_mul_f32 v[146:147], v[146:147], s[16:17] op_sel_hi:[1,0]
	v_pk_mul_f32 v[140:141], v[140:141], s[16:17] op_sel_hi:[1,0]
	v_pk_mul_f32 v[142:143], v[142:143], s[16:17] op_sel_hi:[1,0]
	v_max_f32_e32 v144, 0xda24260, v144
	v_max_f32_e32 v145, 0xda24260, v145
	v_max_f32_e32 v146, 0xda24260, v146
	v_max_f32_e32 v147, 0xda24260, v147
	v_rcp_f32_e32 v144, v144
	v_rcp_f32_e32 v145, v145
	v_rcp_f32_e32 v146, v146
	v_rcp_f32_e32 v147, v147
	v_pk_mul_f32 v[140:141], v[140:141], v[144:145]
	v_pk_mul_f32 v[142:143], v[142:143], v[146:147]
	v_pk_mul_f32 v[44:45], v[44:45], v[140:141]
	v_pk_mul_f32 v[46:47], v[46:47], v[142:143]
	v_cvt_f32_ubyte0_e32 v144, v183
	v_cvt_f32_ubyte1_e32 v145, v183
	v_cvt_f32_ubyte2_e32 v146, v183
	v_cvt_f32_ubyte3_e32 v147, v183
	v_cvt_f32_ubyte0_e32 v140, v179
	v_cvt_f32_ubyte1_e32 v141, v179
	v_cvt_f32_ubyte2_e32 v142, v179
	v_cvt_f32_ubyte3_e32 v143, v179
	v_pk_mul_f32 v[144:145], v[144:145], s[16:17] op_sel_hi:[1,0]
	v_pk_mul_f32 v[146:147], v[146:147], s[16:17] op_sel_hi:[1,0]
	v_pk_mul_f32 v[140:141], v[140:141], s[16:17] op_sel_hi:[1,0]
	v_pk_mul_f32 v[142:143], v[142:143], s[16:17] op_sel_hi:[1,0]
	v_max_f32_e32 v144, 0xda24260, v144
	v_max_f32_e32 v145, 0xda24260, v145
	v_max_f32_e32 v146, 0xda24260, v146
	v_max_f32_e32 v147, 0xda24260, v147
	v_rcp_f32_e32 v144, v144
	v_rcp_f32_e32 v145, v145
	v_rcp_f32_e32 v146, v146
	v_rcp_f32_e32 v147, v147
	v_pk_mul_f32 v[140:141], v[140:141], v[144:145]
	v_pk_mul_f32 v[142:143], v[142:143], v[146:147]
	v_pk_mul_f32 v[36:37], v[36:37], v[140:141]
	v_pk_mul_f32 v[38:39], v[38:39], v[142:143]
	s_waitcnt vmcnt(6)
; __device__ __forceinline__ float u8f(unsigned w, int i) { return (float)((w >> (8 * i)) & 0xffu) * (1.f / 255.f); }
; __device__ void phase4(const Params& p) {
;     ...
;             #pragma unroll
;             for (int ai = 0; ai < 2; ++ai)
;               #pragma unroll
;               for (int m = 0; m < 4; ++m) {
;                 const unsigned ga = pa[(ai * 128 + m * 16) / 4];
;                 const unsigned gb = pb[(ai * 128 + m * 16) / 4];
;                 #pragma unroll
;                 for (int j = 0; j < 4; ++j)
;                   acc[ai][bj][m][n][j] *= u8f(ga, j) * __builtin_amdgcn_rcpf(fmaxf(u8f(gb, j), 1e-30f));
;               }
	v_permlane16_swap_b32 v184, v185
	v_permlane16_swap_b32 v186, v187
	v_permlane16_swap_b32 v188, v189
	v_permlane16_swap_b32 v190, v191
	v_permlane32_swap_b32 v184, v186
	v_permlane32_swap_b32 v185, v187
	v_permlane32_swap_b32 v188, v190
	v_permlane32_swap_b32 v189, v191
	v_cvt_f32_ubyte0_e32 v144, v188
	v_cvt_f32_ubyte1_e32 v145, v188
	v_cvt_f32_ubyte2_e32 v146, v188
	v_cvt_f32_ubyte3_e32 v147, v188
	v_cvt_f32_ubyte0_e32 v140, v184
	v_cvt_f32_ubyte1_e32 v141, v184
	v_cvt_f32_ubyte2_e32 v142, v184
	v_cvt_f32_ubyte3_e32 v143, v184
	v_pk_mul_f32 v[144:145], v[144:145], s[16:17] op_sel_hi:[1,0]
	v_pk_mul_f32 v[146:147], v[146:147], s[16:17] op_sel_hi:[1,0]
	v_pk_mul_f32 v[140:141], v[140:141], s[16:17] op_sel_hi:[1,0]
	v_pk_mul_f32 v[142:143], v[142:143], s[16:17] op_sel_hi:[1,0]
	v_max_f32_e32 v144, 0xda24260, v144
	v_max_f32_e32 v145, 0xda24260, v145
	v_max_f32_e32 v146, 0xda24260, v146
	v_max_f32_e32 v147, 0xda24260, v147
	v_rcp_f32_e32 v144, v144
	v_rcp_f32_e32 v145, v145
	v_rcp_f32_e32 v146, v146
	v_rcp_f32_e32 v147, v147
	v_pk_mul_f32 v[140:141], v[140:141], v[144:145]
	v_pk_mul_f32 v[142:143], v[142:143], v[146:147]
	v_pk_mul_f32 v[96:97], v[96:97], v[140:141]
	v_pk_mul_f32 v[98:99], v[98:99], v[142:143]
	v_cvt_f32_ubyte0_e32 v144, v189
	v_cvt_f32_ubyte1_e32 v145, v189
	v_cvt_f32_ubyte2_e32 v146, v189
	v_cvt_f32_ubyte3_e32 v147, v189
	v_cvt_f32_ubyte0_e32 v140, v185
	v_cvt_f32_ubyte1_e32 v141, v185
	v_cvt_f32_ubyte2_e32 v142, v185
	v_cvt_f32_ubyte3_e32 v143, v185
	v_pk_mul_f32 v[144:145], v[144:145], s[16:17] op_sel_hi:[1,0]
	v_pk_mul_f32 v[146:147], v[146:147], s[16:17] op_sel_hi:[1,0]
	v_pk_mul_f32 v[140:141], v[140:141], s[16:17] op_sel_hi:[1,0]
	v_pk_mul_f32 v[142:143], v[142:143], s[16:17] op_sel_hi:[1,0]
	v_max_f32_e32 v144, 0xda24260, v144
	v_max_f32_e32 v145, 0xda24260, v145
	v_max_f32_e32 v146, 0xda24260, v146
	v_max_f32_e32 v147, 0xda24260, v147
	v_rcp_f32_e32 v144, v144
	v_rcp_f32_e32 v145, v145
	v_rcp_f32_e32 v146, v146
	v_rcp_f32_e32 v147, v147
	v_pk_mul_f32 v[140:141], v[140:141], v[144:145]
	v_pk_mul_f32 v[142:143], v[142:143], v[146:147]
	v_pk_mul_f32 v[88:89], v[88:89], v[140:141]
	v_pk_mul_f32 v[90:91], v[90:91], v[142:143]
	v_cvt_f32_ubyte0_e32 v144, v190
	v_cvt_f32_ubyte1_e32 v145, v190
	v_cvt_f32_ubyte2_e32 v146, v190
	v_cvt_f32_ubyte3_e32 v147, v190
	v_cvt_f32_ubyte0_e32 v140, v186
	v_cvt_f32_ubyte1_e32 v141, v186
	v_cvt_f32_ubyte2_e32 v142, v186
	v_cvt_f32_ubyte3_e32 v143, v186
	v_pk_mul_f32 v[144:145], v[144:145], s[16:17] op_sel_hi:[1,0]
	v_pk_mul_f32 v[146:147], v[146:147], s[16:17] op_sel_hi:[1,0]
	v_pk_mul_f32 v[140:141], v[140:141], s[16:17] op_sel_hi:[1,0]
	v_pk_mul_f32 v[142:143], v[142:143], s[16:17] op_sel_hi:[1,0]
	v_max_f32_e32 v144, 0xda24260, v144
	v_max_f32_e32 v145, 0xda24260, v145
	v_max_f32_e32 v146, 0xda24260, v146
	v_max_f32_e32 v147, 0xda24260, v147
	v_rcp_f32_e32 v144, v144
	v_rcp_f32_e32 v145, v145
	v_rcp_f32_e32 v146, v146
	v_rcp_f32_e32 v147, v147
	v_pk_mul_f32 v[140:141], v[140:141], v[144:145]
	v_pk_mul_f32 v[142:143], v[142:143], v[146:147]
	v_pk_mul_f32 v[80:81], v[80:81], v[140:141]
	v_pk_mul_f32 v[82:83], v[82:83], v[142:143]
	v_cvt_f32_ubyte0_e32 v144, v191
	v_cvt_f32_ubyte1_e32 v145, v191
	v_cvt_f32_ubyte2_e32 v146, v191
	v_cvt_f32_ubyte3_e32 v147, v191
	v_cvt_f32_ubyte0_e32 v140, v187
	v_cvt_f32_ubyte1_e32 v141, v187
	v_cvt_f32_ubyte2_e32 v142, v187
	v_cvt_f32_ubyte3_e32 v143, v187
	v_pk_mul_f32 v[144:145], v[144:145], s[16:17] op_sel_hi:[1,0]
	v_pk_mul_f32 v[146:147], v[146:147], s[16:17] op_sel_hi:[1,0]
	v_pk_mul_f32 v[140:141], v[140:141], s[16:17] op_sel_hi:[1,0]
	v_pk_mul_f32 v[142:143], v[142:143], s[16:17] op_sel_hi:[1,0]
	v_max_f32_e32 v144, 0xda24260, v144
	v_max_f32_e32 v145, 0xda24260, v145
	v_max_f32_e32 v146, 0xda24260, v146
	v_max_f32_e32 v147, 0xda24260, v147
	v_rcp_f32_e32 v144, v144
	v_rcp_f32_e32 v145, v145
	v_rcp_f32_e32 v146, v146
	v_rcp_f32_e32 v147, v147
	v_pk_mul_f32 v[140:141], v[140:141], v[144:145]
	v_pk_mul_f32 v[142:143], v[142:143], v[146:147]
	v_pk_mul_f32 v[72:73], v[72:73], v[140:141]
	v_pk_mul_f32 v[74:75], v[74:75], v[142:143]
	s_waitcnt vmcnt(4)
	v_permlane16_swap_b32 v196, v197
	v_permlane16_swap_b32 v198, v199
	v_permlane16_swap_b32 v200, v201
	v_permlane16_swap_b32 v202, v203
	v_permlane32_swap_b32 v196, v198
	v_permlane32_swap_b32 v197, v199
	v_permlane32_swap_b32 v200, v202
	v_permlane32_swap_b32 v201, v203
	v_cvt_f32_ubyte0_e32 v144, v200
	v_cvt_f32_ubyte1_e32 v145, v200
	v_cvt_f32_ubyte2_e32 v146, v200
	v_cvt_f32_ubyte3_e32 v147, v200
	v_cvt_f32_ubyte0_e32 v140, v196
	v_cvt_f32_ubyte1_e32 v141, v196
	v_cvt_f32_ubyte2_e32 v142, v196
	v_cvt_f32_ubyte3_e32 v143, v196
	v_pk_mul_f32 v[144:145], v[144:145], s[16:17] op_sel_hi:[1,0]
	v_pk_mul_f32 v[146:147], v[146:147], s[16:17] op_sel_hi:[1,0]
	v_pk_mul_f32 v[140:141], v[140:141], s[16:17] op_sel_hi:[1,0]
	v_pk_mul_f32 v[142:143], v[142:143], s[16:17] op_sel_hi:[1,0]
	v_max_f32_e32 v144, 0xda24260, v144
	v_max_f32_e32 v145, 0xda24260, v145
	v_max_f32_e32 v146, 0xda24260, v146
	v_max_f32_e32 v147, 0xda24260, v147
	v_rcp_f32_e32 v144, v144
	v_rcp_f32_e32 v145, v145
	v_rcp_f32_e32 v146, v146
	v_rcp_f32_e32 v147, v147
	v_pk_mul_f32 v[140:141], v[140:141], v[144:145]
	v_pk_mul_f32 v[142:143], v[142:143], v[146:147]
	v_pk_mul_f32 v[32:33], v[32:33], v[140:141]
	v_pk_mul_f32 v[34:35], v[34:35], v[142:143]
	v_cvt_f32_ubyte0_e32 v144, v201
	v_cvt_f32_ubyte1_e32 v145, v201
	v_cvt_f32_ubyte2_e32 v146, v201
	v_cvt_f32_ubyte3_e32 v147, v201
	v_cvt_f32_ubyte0_e32 v140, v197
	v_cvt_f32_ubyte1_e32 v141, v197
	v_cvt_f32_ubyte2_e32 v142, v197
	v_cvt_f32_ubyte3_e32 v143, v197
	v_pk_mul_f32 v[144:145], v[144:145], s[16:17] op_sel_hi:[1,0]
; __device__ __forceinline__ float u8f(unsigned w, int i) { return (float)((w >> (8 * i)) & 0xffu) * (1.f / 255.f); }
; __device__ void phase4(const Params& p) {
;     ...
;             #pragma unroll
;             for (int ai = 0; ai < 2; ++ai)
;               #pragma unroll
;               for (int m = 0; m < 4; ++m) {
;                 const unsigned ga = pa[(ai * 128 + m * 16) / 4];
;                 const unsigned gb = pb[(ai * 128 + m * 16) / 4];
;                 #pragma unroll
;                 for (int j = 0; j < 4; ++j)
;                   acc[ai][bj][m][n][j] *= u8f(ga, j) * __builtin_amdgcn_rcpf(fmaxf(u8f(gb, j), 1e-30f));
;               }
	v_pk_mul_f32 v[146:147], v[146:147], s[16:17] op_sel_hi:[1,0]
	v_pk_mul_f32 v[140:141], v[140:141], s[16:17] op_sel_hi:[1,0]
	v_pk_mul_f32 v[142:143], v[142:143], s[16:17] op_sel_hi:[1,0]
	v_max_f32_e32 v144, 0xda24260, v144
	v_max_f32_e32 v145, 0xda24260, v145
	v_max_f32_e32 v146, 0xda24260, v146
	v_max_f32_e32 v147, 0xda24260, v147
	v_rcp_f32_e32 v144, v144
	v_rcp_f32_e32 v145, v145
	v_rcp_f32_e32 v146, v146
	v_rcp_f32_e32 v147, v147
	v_pk_mul_f32 v[140:141], v[140:141], v[144:145]
	v_pk_mul_f32 v[142:143], v[142:143], v[146:147]
	v_pk_mul_f32 v[24:25], v[24:25], v[140:141]
	v_pk_mul_f32 v[26:27], v[26:27], v[142:143]
	v_cvt_f32_ubyte0_e32 v144, v202
	v_cvt_f32_ubyte1_e32 v145, v202
	v_cvt_f32_ubyte2_e32 v146, v202
	v_cvt_f32_ubyte3_e32 v147, v202
	v_cvt_f32_ubyte0_e32 v140, v198
	v_cvt_f32_ubyte1_e32 v141, v198
	v_cvt_f32_ubyte2_e32 v142, v198
	v_cvt_f32_ubyte3_e32 v143, v198
	v_pk_mul_f32 v[144:145], v[144:145], s[16:17] op_sel_hi:[1,0]
	v_pk_mul_f32 v[146:147], v[146:147], s[16:17] op_sel_hi:[1,0]
	v_pk_mul_f32 v[140:141], v[140:141], s[16:17] op_sel_hi:[1,0]
	v_pk_mul_f32 v[142:143], v[142:143], s[16:17] op_sel_hi:[1,0]
	v_max_f32_e32 v144, 0xda24260, v144
	v_max_f32_e32 v145, 0xda24260, v145
	v_max_f32_e32 v146, 0xda24260, v146
	v_max_f32_e32 v147, 0xda24260, v147
	v_rcp_f32_e32 v144, v144
	v_rcp_f32_e32 v145, v145
	v_rcp_f32_e32 v146, v146
	v_rcp_f32_e32 v147, v147
	v_pk_mul_f32 v[140:141], v[140:141], v[144:145]
	v_pk_mul_f32 v[142:143], v[142:143], v[146:147]
	v_pk_mul_f32 v[16:17], v[16:17], v[140:141]
	v_pk_mul_f32 v[18:19], v[18:19], v[142:143]
	v_cvt_f32_ubyte0_e32 v144, v203
	v_cvt_f32_ubyte1_e32 v145, v203
	v_cvt_f32_ubyte2_e32 v146, v203
	v_cvt_f32_ubyte3_e32 v147, v203
	v_cvt_f32_ubyte0_e32 v140, v199
	v_cvt_f32_ubyte1_e32 v141, v199
	v_cvt_f32_ubyte2_e32 v142, v199
	v_cvt_f32_ubyte3_e32 v143, v199
	v_pk_mul_f32 v[144:145], v[144:145], s[16:17] op_sel_hi:[1,0]
	v_pk_mul_f32 v[146:147], v[146:147], s[16:17] op_sel_hi:[1,0]
	v_pk_mul_f32 v[140:141], v[140:141], s[16:17] op_sel_hi:[1,0]
	v_pk_mul_f32 v[142:143], v[142:143], s[16:17] op_sel_hi:[1,0]
	v_max_f32_e32 v144, 0xda24260, v144
	v_max_f32_e32 v145, 0xda24260, v145
	v_max_f32_e32 v146, 0xda24260, v146
	v_max_f32_e32 v147, 0xda24260, v147
	v_rcp_f32_e32 v144, v144
	v_rcp_f32_e32 v145, v145
	v_rcp_f32_e32 v146, v146
	v_rcp_f32_e32 v147, v147
	v_pk_mul_f32 v[140:141], v[140:141], v[144:145]
	v_pk_mul_f32 v[142:143], v[142:143], v[146:147]
	v_pk_mul_f32 v[8:9], v[8:9], v[140:141]
	v_pk_mul_f32 v[10:11], v[10:11], v[142:143]
	s_waitcnt vmcnt(2)
	v_permlane16_swap_b32 v204, v205
	v_permlane16_swap_b32 v206, v207
	v_permlane16_swap_b32 v208, v209
	v_permlane16_swap_b32 v210, v211
	v_permlane32_swap_b32 v204, v206
	v_permlane32_swap_b32 v205, v207
	v_permlane32_swap_b32 v208, v210
	v_permlane32_swap_b32 v209, v211
	v_cvt_f32_ubyte0_e32 v144, v208
	v_cvt_f32_ubyte1_e32 v145, v208
	v_cvt_f32_ubyte2_e32 v146, v208
	v_cvt_f32_ubyte3_e32 v147, v208
	v_cvt_f32_ubyte0_e32 v140, v204
	v_cvt_f32_ubyte1_e32 v141, v204
	v_cvt_f32_ubyte2_e32 v142, v204
	v_cvt_f32_ubyte3_e32 v143, v204
	v_pk_mul_f32 v[144:145], v[144:145], s[16:17] op_sel_hi:[1,0]
	v_pk_mul_f32 v[146:147], v[146:147], s[16:17] op_sel_hi:[1,0]
	v_pk_mul_f32 v[140:141], v[140:141], s[16:17] op_sel_hi:[1,0]
	v_pk_mul_f32 v[142:143], v[142:143], s[16:17] op_sel_hi:[1,0]
	v_max_f32_e32 v144, 0xda24260, v144
	v_max_f32_e32 v145, 0xda24260, v145
	v_max_f32_e32 v146, 0xda24260, v146
	v_max_f32_e32 v147, 0xda24260, v147
	v_rcp_f32_e32 v144, v144
	v_rcp_f32_e32 v145, v145
	v_rcp_f32_e32 v146, v146
	v_rcp_f32_e32 v147, v147
	v_pk_mul_f32 v[140:141], v[140:141], v[144:145]
	v_pk_mul_f32 v[142:143], v[142:143], v[146:147]
	v_pk_mul_f32 v[92:93], v[92:93], v[140:141]
	v_pk_mul_f32 v[94:95], v[94:95], v[142:143]
	v_cvt_f32_ubyte0_e32 v144, v209
	v_cvt_f32_ubyte1_e32 v145, v209
	v_cvt_f32_ubyte2_e32 v146, v209
	v_cvt_f32_ubyte3_e32 v147, v209
	v_cvt_f32_ubyte0_e32 v140, v205
	v_cvt_f32_ubyte1_e32 v141, v205
	v_cvt_f32_ubyte2_e32 v142, v205
	v_cvt_f32_ubyte3_e32 v143, v205
	v_pk_mul_f32 v[144:145], v[144:145], s[16:17] op_sel_hi:[1,0]
	v_pk_mul_f32 v[146:147], v[146:147], s[16:17] op_sel_hi:[1,0]
	v_pk_mul_f32 v[140:141], v[140:141], s[16:17] op_sel_hi:[1,0]
	v_pk_mul_f32 v[142:143], v[142:143], s[16:17] op_sel_hi:[1,0]
	v_max_f32_e32 v144, 0xda24260, v144
	v_max_f32_e32 v145, 0xda24260, v145
	v_max_f32_e32 v146, 0xda24260, v146
	v_max_f32_e32 v147, 0xda24260, v147
	v_rcp_f32_e32 v144, v144
	v_rcp_f32_e32 v145, v145
	v_rcp_f32_e32 v146, v146
	v_rcp_f32_e32 v147, v147
	v_pk_mul_f32 v[140:141], v[140:141], v[144:145]
	v_pk_mul_f32 v[142:143], v[142:143], v[146:147]
	v_pk_mul_f32 v[84:85], v[84:85], v[140:141]
	v_pk_mul_f32 v[86:87], v[86:87], v[142:143]
	v_cvt_f32_ubyte0_e32 v144, v210
	v_cvt_f32_ubyte1_e32 v145, v210
	v_cvt_f32_ubyte2_e32 v146, v210
	v_cvt_f32_ubyte3_e32 v147, v210
	v_cvt_f32_ubyte0_e32 v140, v206
	v_cvt_f32_ubyte1_e32 v141, v206
	v_cvt_f32_ubyte2_e32 v142, v206
	v_cvt_f32_ubyte3_e32 v143, v206
	v_pk_mul_f32 v[144:145], v[144:145], s[16:17] op_sel_hi:[1,0]
	v_pk_mul_f32 v[146:147], v[146:147], s[16:17] op_sel_hi:[1,0]
	v_pk_mul_f32 v[140:141], v[140:141], s[16:17] op_sel_hi:[1,0]
	v_pk_mul_f32 v[142:143], v[142:143], s[16:17] op_sel_hi:[1,0]
	v_max_f32_e32 v144, 0xda24260, v144
	v_max_f32_e32 v145, 0xda24260, v145
	v_max_f32_e32 v146, 0xda24260, v146
	v_max_f32_e32 v147, 0xda24260, v147
	v_rcp_f32_e32 v144, v144
	v_rcp_f32_e32 v145, v145
	v_rcp_f32_e32 v146, v146
	v_rcp_f32_e32 v147, v147
	v_pk_mul_f32 v[140:141], v[140:141], v[144:145]
	v_pk_mul_f32 v[142:143], v[142:143], v[146:147]
	v_pk_mul_f32 v[76:77], v[76:77], v[140:141]
	v_pk_mul_f32 v[78:79], v[78:79], v[142:143]
	v_cvt_f32_ubyte0_e32 v144, v211
	v_cvt_f32_ubyte1_e32 v145, v211
	v_cvt_f32_ubyte2_e32 v146, v211
	v_cvt_f32_ubyte3_e32 v147, v211
	v_cvt_f32_ubyte0_e32 v140, v207
	v_cvt_f32_ubyte1_e32 v141, v207
	v_cvt_f32_ubyte2_e32 v142, v207
	v_cvt_f32_ubyte3_e32 v143, v207
	v_pk_mul_f32 v[144:145], v[144:145], s[16:17] op_sel_hi:[1,0]
	v_pk_mul_f32 v[146:147], v[146:147], s[16:17] op_sel_hi:[1,0]
	v_pk_mul_f32 v[140:141], v[140:141], s[16:17] op_sel_hi:[1,0]
	v_pk_mul_f32 v[142:143], v[142:143], s[16:17] op_sel_hi:[1,0]
	v_max_f32_e32 v144, 0xda24260, v144
	v_max_f32_e32 v145, 0xda24260, v145
	v_max_f32_e32 v146, 0xda24260, v146
	v_max_f32_e32 v147, 0xda24260, v147
	v_rcp_f32_e32 v144, v144
	v_rcp_f32_e32 v145, v145
	v_rcp_f32_e32 v146, v146
	v_rcp_f32_e32 v147, v147
	v_pk_mul_f32 v[140:141], v[140:141], v[144:145]
	v_pk_mul_f32 v[142:143], v[142:143], v[146:147]
	v_pk_mul_f32 v[68:69], v[68:69], v[140:141]
	v_pk_mul_f32 v[70:71], v[70:71], v[142:143]
	s_waitcnt vmcnt(0)
; __device__ __forceinline__ float u8f(unsigned w, int i) { return (float)((w >> (8 * i)) & 0xffu) * (1.f / 255.f); }
; __device__ void phase4(const Params& p) {
;     ...
;             #pragma unroll
;             for (int ai = 0; ai < 2; ++ai)
;               #pragma unroll
;               for (int m = 0; m < 4; ++m) {
;                 const unsigned ga = pa[(ai * 128 + m * 16) / 4];
;                 const unsigned gb = pb[(ai * 128 + m * 16) / 4];
;                 #pragma unroll
;                 for (int j = 0; j < 4; ++j)
;                   acc[ai][bj][m][n][j] *= u8f(ga, j) * __builtin_amdgcn_rcpf(fmaxf(u8f(gb, j), 1e-30f));
;               }
	v_permlane16_swap_b32 v212, v213
	v_permlane16_swap_b32 v214, v215
	v_permlane16_swap_b32 v216, v217
	v_permlane16_swap_b32 v218, v219
	v_permlane32_swap_b32 v212, v214
	v_permlane32_swap_b32 v213, v215
	v_permlane32_swap_b32 v216, v218
	v_permlane32_swap_b32 v217, v219
	v_cvt_f32_ubyte0_e32 v144, v216
	v_cvt_f32_ubyte1_e32 v145, v216
	v_cvt_f32_ubyte2_e32 v146, v216
	v_cvt_f32_ubyte3_e32 v147, v216
	v_cvt_f32_ubyte0_e32 v140, v212
	v_cvt_f32_ubyte1_e32 v141, v212
	v_cvt_f32_ubyte2_e32 v142, v212
	v_cvt_f32_ubyte3_e32 v143, v212
	v_pk_mul_f32 v[144:145], v[144:145], s[16:17] op_sel_hi:[1,0]
	v_pk_mul_f32 v[146:147], v[146:147], s[16:17] op_sel_hi:[1,0]
	v_pk_mul_f32 v[140:141], v[140:141], s[16:17] op_sel_hi:[1,0]
	v_pk_mul_f32 v[142:143], v[142:143], s[16:17] op_sel_hi:[1,0]
	v_max_f32_e32 v144, 0xda24260, v144
	v_max_f32_e32 v145, 0xda24260, v145
	v_max_f32_e32 v146, 0xda24260, v146
	v_max_f32_e32 v147, 0xda24260, v147
	v_rcp_f32_e32 v144, v144
	v_rcp_f32_e32 v145, v145
	v_rcp_f32_e32 v146, v146
	v_rcp_f32_e32 v147, v147
	v_pk_mul_f32 v[140:141], v[140:141], v[144:145]
	v_pk_mul_f32 v[142:143], v[142:143], v[146:147]
	v_pk_mul_f32 v[28:29], v[28:29], v[140:141]
	v_pk_mul_f32 v[30:31], v[30:31], v[142:143]
	v_cvt_f32_ubyte0_e32 v144, v217
	v_cvt_f32_ubyte1_e32 v145, v217
	v_cvt_f32_ubyte2_e32 v146, v217
	v_cvt_f32_ubyte3_e32 v147, v217
	v_cvt_f32_ubyte0_e32 v140, v213
	v_cvt_f32_ubyte1_e32 v141, v213
	v_cvt_f32_ubyte2_e32 v142, v213
	v_cvt_f32_ubyte3_e32 v143, v213
	v_pk_mul_f32 v[144:145], v[144:145], s[16:17] op_sel_hi:[1,0]
	v_pk_mul_f32 v[146:147], v[146:147], s[16:17] op_sel_hi:[1,0]
	v_pk_mul_f32 v[140:141], v[140:141], s[16:17] op_sel_hi:[1,0]
	v_pk_mul_f32 v[142:143], v[142:143], s[16:17] op_sel_hi:[1,0]
	v_max_f32_e32 v144, 0xda24260, v144
	v_max_f32_e32 v145, 0xda24260, v145
	v_max_f32_e32 v146, 0xda24260, v146
	v_max_f32_e32 v147, 0xda24260, v147
	v_rcp_f32_e32 v144, v144
	v_rcp_f32_e32 v145, v145
	v_rcp_f32_e32 v146, v146
	v_rcp_f32_e32 v147, v147
	v_pk_mul_f32 v[140:141], v[140:141], v[144:145]
	v_pk_mul_f32 v[142:143], v[142:143], v[146:147]
	v_pk_mul_f32 v[20:21], v[20:21], v[140:141]
	v_pk_mul_f32 v[22:23], v[22:23], v[142:143]
	v_cvt_f32_ubyte0_e32 v144, v218
	v_cvt_f32_ubyte1_e32 v145, v218
	v_cvt_f32_ubyte2_e32 v146, v218
	v_cvt_f32_ubyte3_e32 v147, v218
	v_cvt_f32_ubyte0_e32 v140, v214
	v_cvt_f32_ubyte1_e32 v141, v214
	v_cvt_f32_ubyte2_e32 v142, v214
	v_cvt_f32_ubyte3_e32 v143, v214
	v_pk_mul_f32 v[144:145], v[144:145], s[16:17] op_sel_hi:[1,0]
	v_pk_mul_f32 v[146:147], v[146:147], s[16:17] op_sel_hi:[1,0]
	v_pk_mul_f32 v[140:141], v[140:141], s[16:17] op_sel_hi:[1,0]
	v_pk_mul_f32 v[142:143], v[142:143], s[16:17] op_sel_hi:[1,0]
	v_max_f32_e32 v144, 0xda24260, v144
	v_max_f32_e32 v145, 0xda24260, v145
	v_max_f32_e32 v146, 0xda24260, v146
	v_max_f32_e32 v147, 0xda24260, v147
	v_rcp_f32_e32 v144, v144
	v_rcp_f32_e32 v145, v145
	v_rcp_f32_e32 v146, v146
	v_rcp_f32_e32 v147, v147
	v_pk_mul_f32 v[140:141], v[140:141], v[144:145]
	v_pk_mul_f32 v[142:143], v[142:143], v[146:147]
	v_pk_mul_f32 v[12:13], v[12:13], v[140:141]
	v_pk_mul_f32 v[14:15], v[14:15], v[142:143]
	v_cvt_f32_ubyte0_e32 v144, v219
	v_cvt_f32_ubyte1_e32 v145, v219
	v_cvt_f32_ubyte2_e32 v146, v219
	v_cvt_f32_ubyte3_e32 v147, v219
	v_cvt_f32_ubyte0_e32 v140, v215
	v_cvt_f32_ubyte1_e32 v141, v215
	v_cvt_f32_ubyte2_e32 v142, v215
	v_cvt_f32_ubyte3_e32 v143, v215
	v_pk_mul_f32 v[144:145], v[144:145], s[16:17] op_sel_hi:[1,0]
	v_pk_mul_f32 v[146:147], v[146:147], s[16:17] op_sel_hi:[1,0]
	v_pk_mul_f32 v[140:141], v[140:141], s[16:17] op_sel_hi:[1,0]
	v_pk_mul_f32 v[142:143], v[142:143], s[16:17] op_sel_hi:[1,0]
	v_max_f32_e32 v144, 0xda24260, v144
	v_max_f32_e32 v145, 0xda24260, v145
	v_max_f32_e32 v146, 0xda24260, v146
	v_max_f32_e32 v147, 0xda24260, v147
	v_rcp_f32_e32 v144, v144
	v_rcp_f32_e32 v145, v145
	v_rcp_f32_e32 v146, v146
	v_rcp_f32_e32 v147, v147
	v_pk_mul_f32 v[140:141], v[140:141], v[144:145]
	v_pk_mul_f32 v[142:143], v[142:143], v[146:147]
	v_pk_mul_f32 v[4:5], v[4:5], v[140:141]
	v_pk_mul_f32 v[6:7], v[6:7], v[142:143]
	s_branch .LBB0_599

; __device__ __forceinline__ void gemm_tile(const u16* __restrict__ A, const u16* __restrict__ Bt, const int K,
;                                           const int brow, const int bcol, f32x4 (&acc)[2][2][4][2],
;                                           const bool ZERO_INIT = true) {
;     ...
;   STAGE(SB(0, 0), Bt, bcol, 0); STAGE(SA(0, 0), A, brow, 0);
;   STAGE(SB(0, 1), Bt, bcol + HALF, 0); STAGE(SA(0, 1), A, brow + HALF, 0);
; __device__ __forceinline__ bool tile_coords(int it, int nM, int nN, int& pm, int& pn) {
;   const int G = gridDim.x, b = blockIdx.x, ntiles = nM * nN;
;   int L;
;   if ((G & 7) == 0 && (it + 1) * G <= ntiles) L = it * G + (b & 7) * (G >> 3) + (b >> 3);
;   else L = it * G + b;
;   if (L >= ntiles) return false;
;   const int nig = 8 * nN, gid = L / nig, fm = gid * 8, gsz = min(nM - fm, 8);
;   pm = fm + (L % nig) % gsz;
;   pn = (L % nig) / gsz;
;   return true;
.Lp4n_base:
	s_add_i32 s24, s55, s25
	s_mov_b32 s100, 0
	s_cmpk_gt_i32 s24, 0x4ff
	s_cbranch_scc1 .Lp4n_done
	s_lshr_b32 s25, s24, 6
	s_and_b32 s54, s24, 7
	s_lshl_b32 s25, s25, 3
	s_add_i32 s25, s25, s54
	s_lshl_b32 s25, s25, 8
	s_bfe_u32 s54, s24, 0x30003
	s_lshl_b32 s54, s54, 8
	v_lshrrev_b32_e32 v248, 1, v246
	v_lshrrev_b32_e32 v250, 10, v248
	v_and_b32_e32 v248, 0x3ff, v248
	v_lshl_add_u32 v248, v250, 11, v248
	v_lshlrev_b32_e32 v250, 1, v248
	v_lshrrev_b32_e32 v249, 1, v247
	v_lshrrev_b32_e32 v251, 10, v249
	v_and_b32_e32 v249, 0x3ff, v249
	v_lshl_add_u32 v249, v251, 11, v249
	v_lshlrev_b32_e32 v251, 1, v249
	s_lshl_b32 s55, s25, 12
	s_add_u32 s58, s28, s55
	s_addc_u32 s59, s29, 0
	s_or_b32 s55, s25, 0x80
	s_lshl_b32 s55, s55, 12
	s_add_u32 s60, s28, s55
	s_addc_u32 s61, s29, 0
	s_lshl_b32 s55, s54, 12
	s_add_u32 s55, s55, 0x2900000
	s_add_u32 s62, s30, s55
	s_addc_u32 s63, s31, 0
	s_or_b32 s55, s54, 0x80
	s_lshl_b32 s55, s55, 12
	s_add_u32 s55, s55, 0x2900000
	s_add_u32 s64, s30, s55
	s_addc_u32 s65, s31, 0
	v_lshrrev_b32_e32 v252, 6, v194
	s_nop 0
	v_readfirstlane_b32 s66, v252
	s_nop 3
	s_lshl_b32 s66, s66, 10
	s_add_u32 m0, s66, 0x10000
	s_nop 0
	global_load_lds_dwordx4 v250, s[58:59]
	s_add_u32 m0, s66, 0x12000
	s_nop 0
	global_load_lds_dwordx4 v251, s[58:59]
	s_add_u32 m0, s66, 0x0
	s_nop 0
	global_load_lds_dwordx4 v250, s[62:63]
	s_add_u32 m0, s66, 0x2000
	s_nop 0
	global_load_lds_dwordx4 v251, s[62:63]
	s_add_u32 m0, s66, 0x14000
	s_nop 0
	global_load_lds_dwordx4 v250, s[60:61]
	s_add_u32 m0, s66, 0x16000
	s_nop 0
	global_load_lds_dwordx4 v251, s[60:61]
	s_add_u32 m0, s66, 0x4000
	s_nop 0
	global_load_lds_dwordx4 v250, s[64:65]
	s_add_u32 m0, s66, 0x6000
	s_nop 0
	global_load_lds_dwordx4 v251, s[64:65]
	s_mov_b32 s100, 1
